# baseline (speedup 1.0000x reference)
; #define DSR(dst, addr, OFF) asm volatile("ds_read_b128 %0, %1 offset:%2" : "=&v"(dst) : "v"(addr), "i"(OFF) : "memory")
; template <int EPI>
; __device__ __forceinline__ void gemm_phase(const Params& p, const u16* __restrict__ A, const u16* __restrict__ Bt, int K, int nN,
;                            u16* __restrict__ Cout, int ldc) {
;     ...
;     for (int t = 0; t < nt; ++t) {
;       const int cur = t & 1, nb = cur ^ 1;
;       const bool last = (t + 1 == nt);
;       const bool dostage = !last || has_next;
;       const u16* pa = last ? Abn : Ab + (t + 1) * BK;
;       const u16* pb = last ? Bbn : Bb + (t + 1) * BK;
;       bf16x8 Ar[3], Bq[2][4];
;       const unsigned la_u = lds0 + (unsigned)(cur * STAGE_B + aoff), lb_u = lds0 + (unsigned)(cur * STAGE_B + boff);
;     ...
;       DSR(Bq[0][0], lb_u, 0); DSR(Bq[0][1], lb_u, 2048); DSR(Bq[0][2], lb_u, 4096); DSR(Bq[0][3], lb_u, 6144);
;       DSR(Ar[0], la_u, 0); DSR(Ar[1], la_u, 2048);
;     ...
;       GSTEP(0, 2); GSTEP(1, 6); GSTEP(2, 6); GSTEP(3, 6); GSTEP(4, 2); GSTEP(5, 2); GSTEP(6, 2); GSTEP(7, 2);
;       GSTEP(8, 2); GSTEP(9, 2); GSTEP(10, 2); GSTEP(11, 2); GSTEP(12, 2); GSTEP(13, 2); GSTEP(14, 1); GSTEP(15, 0);
.LBB0_859:
	ds_read_b128 v[0:3], v194 offset:0
	ds_read_b128 v[4:7], v194 offset:0x800
	ds_read_b128 v[8:11], v194 offset:0x1000
	ds_read_b128 v[12:15], v194 offset:0x1800
	ds_read_b128 v[16:19], v193 offset:0
	ds_read_b128 v[20:23], v193 offset:0x800
	ds_read_b128 v[24:27], v193 offset:0x1000
	s_waitcnt lgkmcnt(2)
	s_setprio 1
	v_mfma_f32_16x16x32_bf16 v[28:31], v[16:19], v[0:3], 0
	v_mfma_f32_16x16x32_bf16 v[32:35], v[16:19], v[4:7], 0
	v_mfma_f32_16x16x32_bf16 v[36:39], v[16:19], v[8:11], 0
	v_mfma_f32_16x16x32_bf16 v[16:19], v[16:19], v[12:15], 0
	s_setprio 0
	v_mov_b32_e32 v40, v176
	v_mov_b32_e32 v41, v172
	v_lshl_add_u64 v[40:41], v[40:41], 1, s[30:31]
	v_readfirstlane_b32 s17, v198
	v_lshl_add_u64 v[40:41], v[40:41], 0, s[62:63]
	s_mov_b32 m0, s17
	s_nop 0
	global_load_lds_dwordx4 v[40:41], off
	ds_read_b128 v[40:43], v193 offset:0x1800
	ds_read_b128 v[130:133], v194 offset:0x400
	ds_read_b128 v[134:137], v194 offset:0xc00
	ds_read_b128 v[138:141], v194 offset:0x1400
	ds_read_b128 v[142:145], v194 offset:0x1c00
	s_waitcnt lgkmcnt(6)
	s_setprio 1
	v_mfma_f32_16x16x32_bf16 v[44:47], v[20:23], v[0:3], 0
	v_mfma_f32_16x16x32_bf16 v[48:51], v[20:23], v[4:7], 0
	v_mfma_f32_16x16x32_bf16 v[52:55], v[20:23], v[8:11], 0
	v_mfma_f32_16x16x32_bf16 v[20:23], v[20:23], v[12:15], 0
	s_setprio 0
	v_mov_b32_e32 v56, v178
	v_mov_b32_e32 v57, v172
	v_lshl_add_u64 v[56:57], v[56:57], 1, s[30:31]
	v_readfirstlane_b32 s17, v199
	v_lshl_add_u64 v[56:57], v[56:57], 0, s[62:63]
	s_mov_b32 m0, s17
	s_nop 0
	global_load_lds_dwordx4 v[56:57], off
	ds_read_b128 v[56:59], v193 offset:0x2000
	s_waitcnt lgkmcnt(6)
	s_setprio 1
	v_mfma_f32_16x16x32_bf16 v[60:63], v[24:27], v[0:3], 0
	v_mfma_f32_16x16x32_bf16 v[64:67], v[24:27], v[4:7], 0
	v_mfma_f32_16x16x32_bf16 v[68:71], v[24:27], v[8:11], 0
	v_mfma_f32_16x16x32_bf16 v[24:27], v[24:27], v[12:15], 0
	s_setprio 0
	v_mov_b32_e32 v72, v180
	v_mov_b32_e32 v73, v172
	v_lshl_add_u64 v[72:73], v[72:73], 1, s[30:31]
	v_readfirstlane_b32 s17, v200
	v_lshl_add_u64 v[72:73], v[72:73], 0, s[62:63]
	s_mov_b32 m0, s17
	s_nop 0
	global_load_lds_dwordx4 v[72:73], off
	ds_read_b128 v[72:75], v193 offset:0x2800
	s_waitcnt lgkmcnt(6)
	s_setprio 1
	v_mfma_f32_16x16x32_bf16 v[76:79], v[40:43], v[0:3], 0
	v_mfma_f32_16x16x32_bf16 v[146:149], v[40:43], v[4:7], 0
	v_mfma_f32_16x16x32_bf16 v[150:153], v[40:43], v[8:11], 0
	v_mfma_f32_16x16x32_bf16 v[40:43], v[40:43], v[12:15], 0
	s_setprio 0
	v_mov_b32_e32 v80, v191
	v_mov_b32_e32 v81, v172
	v_lshl_add_u64 v[80:81], v[80:81], 1, s[30:31]
	v_readfirstlane_b32 s17, v201
	v_lshl_add_u64 v[80:81], v[80:81], 0, s[62:63]
	s_mov_b32 m0, s17
	s_nop 0
	global_load_lds_dwordx4 v[80:81], off
	ds_read_b128 v[80:83], v193 offset:0x3000
	s_waitcnt lgkmcnt(2)
	s_setprio 1
	v_mfma_f32_16x16x32_bf16 v[154:157], v[56:59], v[0:3], 0
	v_mfma_f32_16x16x32_bf16 v[158:161], v[56:59], v[4:7], 0
	v_mfma_f32_16x16x32_bf16 v[162:165], v[56:59], v[8:11], 0
	v_mfma_f32_16x16x32_bf16 v[166:169], v[56:59], v[12:15], 0
	s_setprio 0
	v_mov_b32_e32 v56, v176
	v_mov_b32_e32 v57, v172
	v_lshl_add_u64 v[56:57], v[56:57], 1, s[28:29]
	v_readfirstlane_b32 s17, v206
	v_lshl_add_u64 v[56:57], v[56:57], 0, s[62:63]
	s_mov_b32 m0, s17
	s_nop 0
	global_load_lds_dwordx4 v[56:57], off
	ds_read_b128 v[56:59], v193 offset:0x3800
	s_waitcnt lgkmcnt(2)
	s_setprio 1
	v_mfma_f32_16x16x32_bf16 v[208:211], v[72:75], v[0:3], 0
	v_mfma_f32_16x16x32_bf16 v[212:215], v[72:75], v[4:7], 0
	v_mfma_f32_16x16x32_bf16 v[216:219], v[72:75], v[8:11], 0
	v_mfma_f32_16x16x32_bf16 v[220:223], v[72:75], v[12:15], 0
	s_setprio 0
	v_mov_b32_e32 v72, v178
	v_mov_b32_e32 v73, v172
	v_lshl_add_u64 v[72:73], v[72:73], 1, s[28:29]
	v_readfirstlane_b32 s17, v202
	v_lshl_add_u64 v[72:73], v[72:73], 0, s[62:63]
	s_mov_b32 m0, s17
	s_nop 0
	global_load_lds_dwordx4 v[72:73], off
	ds_read_b128 v[72:75], v193 offset:0x400
	s_waitcnt lgkmcnt(2)
	s_setprio 1
	v_mfma_f32_16x16x32_bf16 v[224:227], v[80:83], v[0:3], 0
	v_mfma_f32_16x16x32_bf16 v[228:231], v[80:83], v[4:7], 0
	v_mfma_f32_16x16x32_bf16 v[232:235], v[80:83], v[8:11], 0
	v_mfma_f32_16x16x32_bf16 v[236:239], v[80:83], v[12:15], 0
	s_setprio 0
	v_mov_b32_e32 v80, v180
	v_mov_b32_e32 v81, v172
	v_lshl_add_u64 v[80:81], v[80:81], 1, s[28:29]
	v_readfirstlane_b32 s17, v203
	v_lshl_add_u64 v[80:81], v[80:81], 0, s[62:63]
	s_mov_b32 m0, s17
	s_nop 0
	global_load_lds_dwordx4 v[80:81], off
	ds_read_b128 v[80:83], v193 offset:0xc00
	s_waitcnt lgkmcnt(2)
	s_setprio 1
	v_mfma_f32_16x16x32_bf16 v[0:3], v[56:59], v[0:3], 0
	v_mfma_f32_16x16x32_bf16 v[4:7], v[56:59], v[4:7], 0
	v_mfma_f32_16x16x32_bf16 v[240:243], v[56:59], v[8:11], 0
	v_mfma_f32_16x16x32_bf16 v[244:247], v[56:59], v[12:15], 0
	s_setprio 0
	v_mov_b32_e32 v8, v191
	v_mov_b32_e32 v9, v172
	v_lshl_add_u64 v[8:9], v[8:9], 1, s[28:29]
	v_readfirstlane_b32 s17, v204
	v_lshl_add_u64 v[8:9], v[8:9], 0, s[62:63]
	s_mov_b32 m0, s17
	s_nop 0
	global_load_lds_dwordx4 v[8:9], off
	ds_read_b128 v[8:11], v193 offset:0x1400
	s_waitcnt lgkmcnt(2)
	s_setprio 1
	v_mfma_f32_16x16x32_bf16 v[124:127], v[72:75], v[130:133], v[28:31]
	v_mfma_f32_16x16x32_bf16 v[120:123], v[72:75], v[134:137], v[32:35]
	v_mfma_f32_16x16x32_bf16 v[116:119], v[72:75], v[138:141], v[36:39]
	v_mfma_f32_16x16x32_bf16 v[112:115], v[72:75], v[142:145], v[16:19]
	s_setprio 0
	ds_read_b128 v[12:15], v193 offset:0x1c00
	s_waitcnt lgkmcnt(2)
	s_setprio 1
	v_mfma_f32_16x16x32_bf16 v[108:111], v[80:83], v[130:133], v[44:47]
	v_mfma_f32_16x16x32_bf16 v[104:107], v[80:83], v[134:137], v[48:51]
	v_mfma_f32_16x16x32_bf16 v[100:103], v[80:83], v[138:141], v[52:55]
	v_mfma_f32_16x16x32_bf16 v[96:99], v[80:83], v[142:145], v[20:23]
	s_setprio 0
	ds_read_b128 v[16:19], v193 offset:0x2400
	s_waitcnt lgkmcnt(2)
; __device__ __forceinline__ float rsq_(float x) { return __builtin_amdgcn_rsqf(x); }
; #define WAIT_V(n) asm volatile("s_waitcnt vmcnt(%0)" ::"n"(n) : "memory")
; #define DSR(dst, addr, OFF) asm volatile("ds_read_b128 %0, %1 offset:%2" : "=&v"(dst) : "v"(addr), "i"(OFF) : "memory")
; template <int EPI>
; __device__ __forceinline__ void gemm_phase(const Params& p, const u16* __restrict__ A, const u16* __restrict__ Bt, int K, int nN,
;                            u16* __restrict__ Cout, int ldc) {
;     ...
;     for (int t = 0; t < nt; ++t) {
;       const int cur = t & 1, nb = cur ^ 1;
;       const bool last = (t + 1 == nt);
;       const bool dostage = !last || has_next;
;       const u16* pa = last ? Abn : Ab + (t + 1) * BK;
;       const u16* pb = last ? Bbn : Bb + (t + 1) * BK;
;       bf16x8 Ar[3], Bq[2][4];
;       const unsigned la_u = lds0 + (unsigned)(cur * STAGE_B + aoff), lb_u = lds0 + (unsigned)(cur * STAGE_B + boff);
;     ...
;       DSR(Bq[0][0], lb_u, 0); DSR(Bq[0][1], lb_u, 2048); DSR(Bq[0][2], lb_u, 4096); DSR(Bq[0][3], lb_u, 6144);
;       DSR(Ar[0], la_u, 0); DSR(Ar[1], la_u, 2048);
;     ...
;       GSTEP(0, 2); GSTEP(1, 6); GSTEP(2, 6); GSTEP(3, 6); GSTEP(4, 2); GSTEP(5, 2); GSTEP(6, 2); GSTEP(7, 2);
;       GSTEP(8, 2); GSTEP(9, 2); GSTEP(10, 2); GSTEP(11, 2); GSTEP(12, 2); GSTEP(13, 2); GSTEP(14, 1); GSTEP(15, 0);
;       WAIT_V(0);
;       if (EPI != EPI_SS && t == 0 && tid < 256) rsl[tid] = rsq_(ssv * (1.f / DM) + EPS);
;       __syncthreads();
	s_setprio 1
	v_mfma_f32_16x16x32_bf16 v[92:95], v[8:11], v[130:133], v[60:63]
	v_mfma_f32_16x16x32_bf16 v[88:91], v[8:11], v[134:137], v[64:67]
	v_mfma_f32_16x16x32_bf16 v[84:87], v[8:11], v[138:141], v[68:71]
	v_mfma_f32_16x16x32_bf16 v[80:83], v[8:11], v[142:145], v[24:27]
	s_setprio 0
	ds_read_b128 v[8:11], v193 offset:0x2c00
	s_waitcnt lgkmcnt(2)
	s_setprio 1
	v_mfma_f32_16x16x32_bf16 v[76:79], v[12:15], v[130:133], v[76:79]
	v_mfma_f32_16x16x32_bf16 v[72:75], v[12:15], v[134:137], v[146:149]
	v_mfma_f32_16x16x32_bf16 v[68:71], v[12:15], v[138:141], v[150:153]
	v_mfma_f32_16x16x32_bf16 v[64:67], v[12:15], v[142:145], v[40:43]
	s_setprio 0
	ds_read_b128 v[12:15], v193 offset:0x3400
	s_waitcnt lgkmcnt(2)
	s_setprio 1
	v_mfma_f32_16x16x32_bf16 v[60:63], v[16:19], v[130:133], v[154:157]
	v_mfma_f32_16x16x32_bf16 v[56:59], v[16:19], v[134:137], v[158:161]
	v_mfma_f32_16x16x32_bf16 v[52:55], v[16:19], v[138:141], v[162:165]
	v_mfma_f32_16x16x32_bf16 v[48:51], v[16:19], v[142:145], v[166:169]
	s_setprio 0
	ds_read_b128 v[146:149], v193 offset:0x3c00
	s_waitcnt lgkmcnt(2)
	s_setprio 1
	v_mfma_f32_16x16x32_bf16 v[44:47], v[8:11], v[130:133], v[208:211]
	v_mfma_f32_16x16x32_bf16 v[40:43], v[8:11], v[134:137], v[212:215]
	v_mfma_f32_16x16x32_bf16 v[36:39], v[8:11], v[138:141], v[216:219]
	v_mfma_f32_16x16x32_bf16 v[32:35], v[8:11], v[142:145], v[220:223]
	s_setprio 0
	s_waitcnt lgkmcnt(1)
	s_setprio 1
	v_mfma_f32_16x16x32_bf16 v[28:31], v[12:15], v[130:133], v[224:227]
	v_mfma_f32_16x16x32_bf16 v[24:27], v[12:15], v[134:137], v[228:231]
	v_mfma_f32_16x16x32_bf16 v[20:23], v[12:15], v[138:141], v[232:235]
	v_mfma_f32_16x16x32_bf16 v[16:19], v[12:15], v[142:145], v[236:239]
	s_setprio 0
	s_waitcnt lgkmcnt(0)
	s_setprio 1
	v_mfma_f32_16x16x32_bf16 v[12:15], v[146:149], v[130:133], v[0:3]
	v_mfma_f32_16x16x32_bf16 v[8:11], v[146:149], v[134:137], v[4:7]
	v_mfma_f32_16x16x32_bf16 v[4:7], v[146:149], v[138:141], v[240:243]
	v_mfma_f32_16x16x32_bf16 v[0:3], v[146:149], v[142:145], v[244:247]
	s_setprio 0
	s_waitcnt vmcnt(0)
	s_and_saveexec_b64 s[28:29], s[0:1]
	v_fmamk_f32 v128, v128, 0x3a800000, v183
	s_nop 0
	v_rsq_f32_e32 v128, v128
	s_nop 0
	ds_write_b32 v195, v128
	s_or_b64 exec, exec, s[28:29]
	s_add_u32 s17, s42, s26
	s_addc_u32 s19, s43, s27
	s_add_u32 s30, s44, s2
	s_addc_u32 s31, s45, s3
	s_mov_b32 s34, -15
	s_waitcnt vmcnt(0) lgkmcnt(0)
	s_barrier
	v_readfirstlane_b32 s36, v175
	s_nop 3
	s_lshr_b32 s36, s36, 12
	s_cmp_eq_u32 s36, 1
	s_cbranch_scc0 .Lwi_prio
	s_setprio 1
.Lwi_prio:
	v_or_b32_e32 v209, 0x10000, v194
	v_add_u32_e32 v207, 0x10000, v193
	ds_read_b128 v[212:215], v209 offset:0
	ds_read_b128 v[216:219], v209 offset:2048
	ds_read_b128 v[220:223], v209 offset:4096
	ds_read_b128 v[224:227], v209 offset:6144
	ds_read_b128 v[228:231], v207 offset:0
	ds_read_b128 v[168:171], v207 offset:2048
	ds_read_b128 v[160:163], v207 offset:4096
	v_readfirstlane_b32 s35, v175
	v_lshlrev_b32_e32 v232, 1, v176
	v_lshlrev_b32_e32 v233, 1, v178
	v_lshlrev_b32_e32 v234, 1, v180
	v_lshlrev_b32_e32 v235, 1, v191
	s_cmp_lg_u32 s34, -1
	s_cselect_b32 s28, s30, s22
	s_cselect_b32 s29, s31, s23
	s_cselect_b32 s26, s17, s24
	s_cselect_b32 s27, s19, s25
	s_cselect_b64 vcc, -1, s[20:21]
.Lwi_head:
	s_waitcnt lgkmcnt(2)
	v_mfma_f32_16x16x32_bf16 v[124:127], v[228:231], v[212:215], v[124:127]
	v_mfma_f32_16x16x32_bf16 v[120:123], v[228:231], v[216:219], v[120:123]
	v_mfma_f32_16x16x32_bf16 v[116:119], v[228:231], v[220:223], v[116:119]
	v_mfma_f32_16x16x32_bf16 v[112:115], v[228:231], v[224:227], v[112:115]
	s_cbranch_vccz .Lwi_sk9
	s_mov_b32 m0, s35
	s_nop 0
	global_load_lds_dwordx4 v232, s[28:29]
	s_add_u32 m0, s35, 0x2000
	s_nop 0
	global_load_lds_dwordx4 v233, s[28:29]
.Lwi_sk9:
	ds_read_b128 v[164:167], v207 offset:6144
	ds_read_b128 v[128:131], v209 offset:1024
	ds_read_b128 v[132:135], v209 offset:3072
	ds_read_b128 v[136:139], v209 offset:5120
	ds_read_b128 v[140:143], v209 offset:7168
	s_waitcnt lgkmcnt(6)
	v_mfma_f32_16x16x32_bf16 v[108:111], v[168:171], v[212:215], v[108:111]
	v_mfma_f32_16x16x32_bf16 v[104:107], v[168:171], v[216:219], v[104:107]
	v_mfma_f32_16x16x32_bf16 v[100:103], v[168:171], v[220:223], v[100:103]
	v_mfma_f32_16x16x32_bf16 v[96:99], v[168:171], v[224:227], v[96:99]
	s_cbranch_vccz .Lwi_sk10
	s_add_u32 m0, s35, 0x4000
	s_nop 0
	global_load_lds_dwordx4 v234, s[28:29]
	s_add_u32 m0, s35, 0x6000
	s_nop 0
	global_load_lds_dwordx4 v235, s[28:29]
.Lwi_sk10:
	ds_read_b128 v[168:171], v207 offset:8192
	s_waitcnt lgkmcnt(6)
	v_mfma_f32_16x16x32_bf16 v[92:95], v[160:163], v[212:215], v[92:95]
	v_mfma_f32_16x16x32_bf16 v[88:91], v[160:163], v[216:219], v[88:91]
	v_mfma_f32_16x16x32_bf16 v[84:87], v[160:163], v[220:223], v[84:87]
	v_mfma_f32_16x16x32_bf16 v[80:83], v[160:163], v[224:227], v[80:83]
	s_cbranch_vccz .Lwi_sk11
	s_add_u32 m0, s35, 0x8000
	s_nop 0
	global_load_lds_dwordx4 v232, s[26:27]
	s_add_u32 m0, s35, 0xa000
	s_nop 0
	global_load_lds_dwordx4 v233, s[26:27]
; __device__ __forceinline__ float rsq_(float x) { return __builtin_amdgcn_rsqf(x); }
; #define WAIT_V(n) asm volatile("s_waitcnt vmcnt(%0)" ::"n"(n) : "memory")
; #define DSR(dst, addr, OFF) asm volatile("ds_read_b128 %0, %1 offset:%2" : "=&v"(dst) : "v"(addr), "i"(OFF) : "memory")
; template <int EPI>
; __device__ __forceinline__ void gemm_phase(const Params& p, const u16* __restrict__ A, const u16* __restrict__ Bt, int K, int nN,
;                            u16* __restrict__ Cout, int ldc) {
;     ...
;     for (int t = 0; t < nt; ++t) {
;       const int cur = t & 1, nb = cur ^ 1;
;       const bool last = (t + 1 == nt);
;       const bool dostage = !last || has_next;
;       const u16* pa = last ? Abn : Ab + (t + 1) * BK;
;       const u16* pb = last ? Bbn : Bb + (t + 1) * BK;
;       bf16x8 Ar[3], Bq[2][4];
;       const unsigned la_u = lds0 + (unsigned)(cur * STAGE_B + aoff), lb_u = lds0 + (unsigned)(cur * STAGE_B + boff);
;     ...
;       DSR(Bq[0][0], lb_u, 0); DSR(Bq[0][1], lb_u, 2048); DSR(Bq[0][2], lb_u, 4096); DSR(Bq[0][3], lb_u, 6144);
;       DSR(Ar[0], la_u, 0); DSR(Ar[1], la_u, 2048);
;     ...
;       GSTEP(0, 2); GSTEP(1, 6); GSTEP(2, 6); GSTEP(3, 6); GSTEP(4, 2); GSTEP(5, 2); GSTEP(6, 2); GSTEP(7, 2);
;       GSTEP(8, 2); GSTEP(9, 2); GSTEP(10, 2); GSTEP(11, 2); GSTEP(12, 2); GSTEP(13, 2); GSTEP(14, 1); GSTEP(15, 0);
;       WAIT_V(0);
;       if (EPI != EPI_SS && t == 0 && tid < 256) rsl[tid] = rsq_(ssv * (1.f / DM) + EPS);
;       __syncthreads();
.Lwi_sk11:
	ds_read_b128 v[160:163], v207 offset:10240
	s_waitcnt lgkmcnt(6)
	v_mfma_f32_16x16x32_bf16 v[76:79], v[164:167], v[212:215], v[76:79]
	v_mfma_f32_16x16x32_bf16 v[72:75], v[164:167], v[216:219], v[72:75]
	v_mfma_f32_16x16x32_bf16 v[68:71], v[164:167], v[220:223], v[68:71]
	v_mfma_f32_16x16x32_bf16 v[64:67], v[164:167], v[224:227], v[64:67]
	s_cbranch_vccz .Lwi_sk12
	s_add_u32 m0, s35, 0xc000
	s_nop 0
	global_load_lds_dwordx4 v234, s[26:27]
	s_add_u32 m0, s35, 0xe000
	s_nop 0
	global_load_lds_dwordx4 v235, s[26:27]
.Lwi_sk12:
	ds_read_b128 v[164:167], v207 offset:12288
	s_waitcnt lgkmcnt(2)
	v_mfma_f32_16x16x32_bf16 v[60:63], v[168:171], v[212:215], v[60:63]
	v_mfma_f32_16x16x32_bf16 v[56:59], v[168:171], v[216:219], v[56:59]
	v_mfma_f32_16x16x32_bf16 v[52:55], v[168:171], v[220:223], v[52:55]
	v_mfma_f32_16x16x32_bf16 v[48:51], v[168:171], v[224:227], v[48:51]
	ds_read_b128 v[168:171], v207 offset:14336
	s_waitcnt lgkmcnt(2)
	v_mfma_f32_16x16x32_bf16 v[44:47], v[160:163], v[212:215], v[44:47]
	v_mfma_f32_16x16x32_bf16 v[40:43], v[160:163], v[216:219], v[40:43]
	v_mfma_f32_16x16x32_bf16 v[36:39], v[160:163], v[220:223], v[36:39]
	v_mfma_f32_16x16x32_bf16 v[32:35], v[160:163], v[224:227], v[32:35]
	ds_read_b128 v[160:163], v207 offset:1024
	s_waitcnt lgkmcnt(2)
	v_mfma_f32_16x16x32_bf16 v[28:31], v[164:167], v[212:215], v[28:31]
	v_mfma_f32_16x16x32_bf16 v[24:27], v[164:167], v[216:219], v[24:27]
	v_mfma_f32_16x16x32_bf16 v[20:23], v[164:167], v[220:223], v[20:23]
	v_mfma_f32_16x16x32_bf16 v[16:19], v[164:167], v[224:227], v[16:19]
	ds_read_b128 v[164:167], v207 offset:3072
	s_waitcnt lgkmcnt(2)
	v_mfma_f32_16x16x32_bf16 v[12:15], v[168:171], v[212:215], v[12:15]
	v_mfma_f32_16x16x32_bf16 v[8:11], v[168:171], v[216:219], v[8:11]
	v_mfma_f32_16x16x32_bf16 v[4:7], v[168:171], v[220:223], v[4:7]
	v_mfma_f32_16x16x32_bf16 v[0:3], v[168:171], v[224:227], v[0:3]
	ds_read_b128 v[144:147], v207 offset:5120
	s_waitcnt lgkmcnt(2)
	v_mfma_f32_16x16x32_bf16 v[124:127], v[160:163], v[128:131], v[124:127]
	v_mfma_f32_16x16x32_bf16 v[120:123], v[160:163], v[132:135], v[120:123]
	v_mfma_f32_16x16x32_bf16 v[116:119], v[160:163], v[136:139], v[116:119]
	v_mfma_f32_16x16x32_bf16 v[112:115], v[160:163], v[140:143], v[112:115]
	ds_read_b128 v[148:151], v207 offset:7168
	s_waitcnt lgkmcnt(2)
	v_mfma_f32_16x16x32_bf16 v[108:111], v[164:167], v[128:131], v[108:111]
	v_mfma_f32_16x16x32_bf16 v[104:107], v[164:167], v[132:135], v[104:107]
	v_mfma_f32_16x16x32_bf16 v[100:103], v[164:167], v[136:139], v[100:103]
	v_mfma_f32_16x16x32_bf16 v[96:99], v[164:167], v[140:143], v[96:99]
	ds_read_b128 v[152:155], v207 offset:9216
	s_waitcnt lgkmcnt(2)
	v_mfma_f32_16x16x32_bf16 v[92:95], v[144:147], v[128:131], v[92:95]
	v_mfma_f32_16x16x32_bf16 v[88:91], v[144:147], v[132:135], v[88:91]
	v_mfma_f32_16x16x32_bf16 v[84:87], v[144:147], v[136:139], v[84:87]
	v_mfma_f32_16x16x32_bf16 v[80:83], v[144:147], v[140:143], v[80:83]
	ds_read_b128 v[144:147], v207 offset:11264
	s_waitcnt lgkmcnt(2)
	v_mfma_f32_16x16x32_bf16 v[76:79], v[148:151], v[128:131], v[76:79]
	v_mfma_f32_16x16x32_bf16 v[72:75], v[148:151], v[132:135], v[72:75]
	v_mfma_f32_16x16x32_bf16 v[68:71], v[148:151], v[136:139], v[68:71]
	v_mfma_f32_16x16x32_bf16 v[64:67], v[148:151], v[140:143], v[64:67]
	ds_read_b128 v[148:151], v207 offset:13312
	s_waitcnt lgkmcnt(2)
	v_mfma_f32_16x16x32_bf16 v[60:63], v[152:155], v[128:131], v[60:63]
	v_mfma_f32_16x16x32_bf16 v[56:59], v[152:155], v[132:135], v[56:59]
	v_mfma_f32_16x16x32_bf16 v[52:55], v[152:155], v[136:139], v[52:55]
	v_mfma_f32_16x16x32_bf16 v[48:51], v[152:155], v[140:143], v[48:51]
	ds_read_b128 v[152:155], v207 offset:15360
	s_waitcnt lgkmcnt(2)
	v_mfma_f32_16x16x32_bf16 v[44:47], v[144:147], v[128:131], v[44:47]
	v_mfma_f32_16x16x32_bf16 v[40:43], v[144:147], v[132:135], v[40:43]
	v_mfma_f32_16x16x32_bf16 v[36:39], v[144:147], v[136:139], v[36:39]
	v_mfma_f32_16x16x32_bf16 v[32:35], v[144:147], v[140:143], v[32:35]
	s_waitcnt vmcnt(0) lgkmcnt(0)
	s_barrier
	v_xor_b32_e32 v209, 0x10000, v209
	v_xor_b32_e32 v207, 0x10000, v207
	ds_read_b128 v[212:215], v209 offset:0
	ds_read_b128 v[216:219], v209 offset:2048
	ds_read_b128 v[220:223], v209 offset:4096
	ds_read_b128 v[224:227], v209 offset:6144
	ds_read_b128 v[228:231], v207 offset:0
	ds_read_b128 v[168:171], v207 offset:2048
	ds_read_b128 v[160:163], v207 offset:4096
	s_add_u32 s30, s30, 0x80
	s_addc_u32 s31, s31, 0
	s_add_u32 s17, s17, 0x80
	s_addc_u32 s19, s19, 0
	s_xor_b32 s35, s35, 0x10000
	s_add_i32 s34, s34, 1
	s_cmp_lg_u32 s34, -1
	s_cselect_b32 s28, s30, s22
	s_cselect_b32 s29, s31, s23
	s_cselect_b32 s26, s17, s24
	s_cselect_b32 s27, s19, s25
	s_cselect_b64 vcc, -1, s[20:21]
	s_cmp_eq_u32 s34, 0
	s_cselect_b64 vcc, 0, vcc
	v_mfma_f32_16x16x32_bf16 v[28:31], v[148:151], v[128:131], v[28:31]
	v_mfma_f32_16x16x32_bf16 v[24:27], v[148:151], v[132:135], v[24:27]
	v_mfma_f32_16x16x32_bf16 v[20:23], v[148:151], v[136:139], v[20:23]
	v_mfma_f32_16x16x32_bf16 v[16:19], v[148:151], v[140:143], v[16:19]
	v_mfma_f32_16x16x32_bf16 v[12:15], v[152:155], v[128:131], v[12:15]
	v_mfma_f32_16x16x32_bf16 v[8:11], v[152:155], v[132:135], v[8:11]
	v_mfma_f32_16x16x32_bf16 v[4:7], v[152:155], v[136:139], v[4:7]
	v_mfma_f32_16x16x32_bf16 v[0:3], v[152:155], v[140:143], v[0:3]
	s_cmp_lg_u32 s34, 0
	s_cbranch_scc1 .Lwi_head
	s_waitcnt lgkmcnt(0)
	s_setprio 0
	s_branch .LBB0_854

; #define WAIT_V(n) asm volatile("s_waitcnt vmcnt(%0)" ::"n"(n) : "memory")
; #define DSR(dst, addr, OFF) asm volatile("ds_read_b128 %0, %1 offset:%2" : "=&v"(dst) : "v"(addr), "i"(OFF) : "memory")
; template <int EPI>
; __device__ __forceinline__ void gemm_phase(const Params& p, const u16* __restrict__ A, const u16* __restrict__ Bt, int K, int nN,
;                            u16* __restrict__ Cout, int ldc) {
;     ...
;     f32x4 acc[8][4];
; #pragma unroll
;     for (int m = 0; m < 8; ++m)
; #pragma unroll
;       for (int n = 0; n < 4; ++n) acc[m][n] = f32x4{0.f, 0.f, 0.f, 0.f};
;     if (!prefetched) {
; #pragma unroll
;       for (int i = 0; i < 8; ++i) GLDS_PIECE(i, Ab, Bb, 0);
;       WAIT_V(0); __syncthreads();
;     }
;     prefetched = has_next;
;     for (int t = 0; t < nt; ++t) {
;       const int cur = t & 1, nb = cur ^ 1;
;       const bool last = (t + 1 == nt);
;       const bool dostage = !last || has_next;
;       const u16* pa = last ? Abn : Ab + (t + 1) * BK;
;       const u16* pb = last ? Bbn : Bb + (t + 1) * BK;
;       bf16x8 Ar[3], Bq[2][4];
;       const unsigned la_u = lds0 + (unsigned)(cur * STAGE_B + aoff), lb_u = lds0 + (unsigned)(cur * STAGE_B + boff);
;     ...
;       DSR(Bq[0][0], lb_u, 0); DSR(Bq[0][1], lb_u, 2048); DSR(Bq[0][2], lb_u, 4096); DSR(Bq[0][3], lb_u, 6144);
;       DSR(Ar[0], la_u, 0); DSR(Ar[1], la_u, 2048);
;     ...
;       GSTEP(0, 2); GSTEP(1, 6); GSTEP(2, 6); GSTEP(3, 6); GSTEP(4, 2); GSTEP(5, 2); GSTEP(6, 2); GSTEP(7, 2);
;       GSTEP(8, 2); GSTEP(9, 2); GSTEP(10, 2); GSTEP(11, 2); GSTEP(12, 2); GSTEP(13, 2); GSTEP(14, 1); GSTEP(15, 0);
.LBB0_1104:
	s_mul_i32 s1, s24, s28
	s_mul_hi_i32 s0, s24, s28
	s_add_u32 s14, s22, s1
	s_addc_u32 s15, s23, s0
	s_mul_i32 s1, s24, s27
	s_mul_hi_i32 s0, s24, s27
	s_add_u32 s16, s25, s1
	v_mov_b32_e32 v0, 0
	s_addc_u32 s17, s26, s0
	s_mov_b32 s29, 0
	s_mov_b64 s[0:1], 0
	s_mov_b32 s30, 0
	v_mov_b32_e32 v1, v0
	v_mov_b32_e32 v2, v0
	v_mov_b32_e32 v3, v0
	v_mov_b32_e32 v4, v0
	v_mov_b32_e32 v5, v0
	v_mov_b32_e32 v6, v0
	v_mov_b32_e32 v7, v0
	v_mov_b32_e32 v8, v0
	v_mov_b32_e32 v9, v0
	v_mov_b32_e32 v10, v0
	v_mov_b32_e32 v11, v0
	v_mov_b32_e32 v12, v0
	v_mov_b32_e32 v13, v0
	v_mov_b32_e32 v14, v0
	v_mov_b32_e32 v15, v0
	v_mov_b32_e32 v16, v0
	v_mov_b32_e32 v17, v0
	v_mov_b32_e32 v18, v0
	v_mov_b32_e32 v19, v0
	v_mov_b32_e32 v20, v0
	v_mov_b32_e32 v21, v0
	v_mov_b32_e32 v22, v0
	v_mov_b32_e32 v23, v0
	v_mov_b32_e32 v24, v0
	v_mov_b32_e32 v25, v0
	v_mov_b32_e32 v26, v0
	v_mov_b32_e32 v27, v0
	v_mov_b32_e32 v28, v0
	v_mov_b32_e32 v29, v0
	v_mov_b32_e32 v30, v0
	v_mov_b32_e32 v31, v0
	v_mov_b32_e32 v32, v0
	v_mov_b32_e32 v33, v0
	v_mov_b32_e32 v34, v0
	v_mov_b32_e32 v35, v0
	v_mov_b32_e32 v36, v0
	v_mov_b32_e32 v37, v0
	v_mov_b32_e32 v38, v0
	v_mov_b32_e32 v39, v0
	v_mov_b32_e32 v40, v0
	v_mov_b32_e32 v41, v0
	v_mov_b32_e32 v42, v0
	v_mov_b32_e32 v43, v0
	v_mov_b32_e32 v44, v0
	v_mov_b32_e32 v45, v0
	v_mov_b32_e32 v46, v0
	v_mov_b32_e32 v47, v0
	v_mov_b32_e32 v48, v0
	v_mov_b32_e32 v49, v0
	v_mov_b32_e32 v50, v0
	v_mov_b32_e32 v51, v0
	v_mov_b32_e32 v52, v0
	v_mov_b32_e32 v53, v0
	v_mov_b32_e32 v54, v0
	v_mov_b32_e32 v55, v0
	v_mov_b32_e32 v56, v0
	v_mov_b32_e32 v57, v0
	v_mov_b32_e32 v58, v0
	v_mov_b32_e32 v59, v0
	v_mov_b32_e32 v60, v0
	v_mov_b32_e32 v61, v0
	v_mov_b32_e32 v62, v0
	v_mov_b32_e32 v63, v0
	v_mov_b32_e32 v64, v0
	v_mov_b32_e32 v65, v0
	v_mov_b32_e32 v66, v0
	v_mov_b32_e32 v67, v0
	v_mov_b32_e32 v68, v0
	v_mov_b32_e32 v69, v0
	v_mov_b32_e32 v70, v0
	v_mov_b32_e32 v71, v0
	v_mov_b32_e32 v72, v0
	v_mov_b32_e32 v73, v0
	v_mov_b32_e32 v74, v0
	v_mov_b32_e32 v75, v0
	v_mov_b32_e32 v76, v0
	v_mov_b32_e32 v77, v0
	v_mov_b32_e32 v78, v0
	v_mov_b32_e32 v79, v0
	v_mov_b32_e32 v80, v0
	v_mov_b32_e32 v81, v0
	v_mov_b32_e32 v82, v0
	v_mov_b32_e32 v83, v0
	v_mov_b32_e32 v84, v0
	v_mov_b32_e32 v85, v0
	v_mov_b32_e32 v86, v0
	v_mov_b32_e32 v87, v0
	v_mov_b32_e32 v88, v0
	v_mov_b32_e32 v89, v0
	v_mov_b32_e32 v90, v0
	v_mov_b32_e32 v91, v0
	v_mov_b32_e32 v92, v0
	v_mov_b32_e32 v93, v0
	v_mov_b32_e32 v94, v0
	v_mov_b32_e32 v95, v0
	v_mov_b32_e32 v96, v0
	v_mov_b32_e32 v97, v0
	v_mov_b32_e32 v98, v0
	v_mov_b32_e32 v99, v0
	v_mov_b32_e32 v100, v0
	v_mov_b32_e32 v101, v0
	v_mov_b32_e32 v102, v0
	v_mov_b32_e32 v103, v0
	v_mov_b32_e32 v104, v0
	v_mov_b32_e32 v105, v0
	v_mov_b32_e32 v106, v0
	v_mov_b32_e32 v107, v0
	v_mov_b32_e32 v108, v0
	v_mov_b32_e32 v109, v0
	v_mov_b32_e32 v110, v0
	v_mov_b32_e32 v111, v0
	v_mov_b32_e32 v112, v0
	v_mov_b32_e32 v113, v0
	v_mov_b32_e32 v114, v0
	v_mov_b32_e32 v115, v0
	v_mov_b32_e32 v116, v0
	v_mov_b32_e32 v117, v0
	v_mov_b32_e32 v118, v0
	v_mov_b32_e32 v119, v0
	v_mov_b32_e32 v120, v0
	v_mov_b32_e32 v121, v0
	v_mov_b32_e32 v122, v0
	v_mov_b32_e32 v123, v0
	v_mov_b32_e32 v124, v0
	v_mov_b32_e32 v125, v0
	v_mov_b32_e32 v126, v0
	v_mov_b32_e32 v127, v0
	s_not_b32 s30, s21
	s_mov_b64 s[34:35], s[16:17]
	s_mov_b64 s[0:1], s[14:15]
	v_readfirstlane_b32 s31, v192
	s_nop 3
	s_lshr_b32 s31, s31, 12
	s_cmp_eq_u32 s31, 1
	s_cbranch_scc0 .Lss_prio
	s_setprio 1
.Lss_prio:
	v_mov_b32_e32 v198, v194
	v_mov_b32_e32 v197, v193
	ds_read_b128 v[212:215], v198 offset:0
	ds_read_b128 v[216:219], v198 offset:2048
	ds_read_b128 v[220:223], v198 offset:4096
	ds_read_b128 v[224:227], v198 offset:6144
	ds_read_b128 v[228:231], v197 offset:0
	ds_read_b128 v[168:171], v197 offset:2048
	ds_read_b128 v[160:163], v197 offset:4096
	v_readfirstlane_b32 s29, v192
	s_add_u32 s29, s29, 0x10000
	v_lshlrev_b32_e32 v232, 1, v174
	v_lshlrev_b32_e32 v233, 1, v176
	v_lshlrev_b32_e32 v234, 1, v178
	v_lshlrev_b32_e32 v235, 1, v180
	s_cmp_lg_u32 s30, -1
	s_cselect_b32 s34, s34, s10
	s_cselect_b32 s35, s35, s11
	s_cselect_b32 s0, s0, s6
	s_cselect_b32 s1, s1, s7
	s_cselect_b64 vcc, -1, s[12:13]
.Lss_head:
	s_waitcnt lgkmcnt(2)
	v_mfma_f32_16x16x32_bf16 v[124:127], v[228:231], v[212:215], v[124:127]
	v_mfma_f32_16x16x32_bf16 v[120:123], v[228:231], v[216:219], v[120:123]
	v_mfma_f32_16x16x32_bf16 v[116:119], v[228:231], v[220:223], v[116:119]
	v_mfma_f32_16x16x32_bf16 v[112:115], v[228:231], v[224:227], v[112:115]
	s_cbranch_vccz .Lss_sk1
	s_mov_b32 m0, s29
	s_nop 0
	global_load_lds_dwordx4 v232, s[34:35]
	s_add_u32 m0, s29, 0x2000
	s_nop 0
	global_load_lds_dwordx4 v233, s[34:35]
.Lss_sk1:
	ds_read_b128 v[164:167], v197 offset:6144
	ds_read_b128 v[128:131], v198 offset:1024
	ds_read_b128 v[132:135], v198 offset:3072
	ds_read_b128 v[136:139], v198 offset:5120
	ds_read_b128 v[140:143], v198 offset:7168
	s_waitcnt lgkmcnt(6)
	v_mfma_f32_16x16x32_bf16 v[108:111], v[168:171], v[212:215], v[108:111]
	v_mfma_f32_16x16x32_bf16 v[104:107], v[168:171], v[216:219], v[104:107]
	v_mfma_f32_16x16x32_bf16 v[100:103], v[168:171], v[220:223], v[100:103]
	v_mfma_f32_16x16x32_bf16 v[96:99], v[168:171], v[224:227], v[96:99]
	s_cbranch_vccz .Lss_sk2
	s_add_u32 m0, s29, 0x4000
	s_nop 0
	global_load_lds_dwordx4 v234, s[34:35]
	s_add_u32 m0, s29, 0x6000
	s_nop 0
	global_load_lds_dwordx4 v235, s[34:35]
.Lss_sk2:
	ds_read_b128 v[168:171], v197 offset:8192
	s_waitcnt lgkmcnt(6)
	v_mfma_f32_16x16x32_bf16 v[92:95], v[160:163], v[212:215], v[92:95]
	v_mfma_f32_16x16x32_bf16 v[88:91], v[160:163], v[216:219], v[88:91]
	v_mfma_f32_16x16x32_bf16 v[84:87], v[160:163], v[220:223], v[84:87]
	v_mfma_f32_16x16x32_bf16 v[80:83], v[160:163], v[224:227], v[80:83]
	s_cbranch_vccz .Lss_sk3
	s_add_u32 m0, s29, 0x8000
	s_nop 0
	global_load_lds_dwordx4 v232, s[0:1]
	s_add_u32 m0, s29, 0xa000
	s_nop 0
	global_load_lds_dwordx4 v233, s[0:1]
; __device__ __forceinline__ float rsq_(float x) { return __builtin_amdgcn_rsqf(x); }
; #define WAIT_V(n) asm volatile("s_waitcnt vmcnt(%0)" ::"n"(n) : "memory")
; #define DSR(dst, addr, OFF) asm volatile("ds_read_b128 %0, %1 offset:%2" : "=&v"(dst) : "v"(addr), "i"(OFF) : "memory")
; template <int EPI>
; __device__ __forceinline__ void gemm_phase(const Params& p, const u16* __restrict__ A, const u16* __restrict__ Bt, int K, int nN,
;                            u16* __restrict__ Cout, int ldc) {
;     ...
;     for (int t = 0; t < nt; ++t) {
;       const int cur = t & 1, nb = cur ^ 1;
;       const bool last = (t + 1 == nt);
;       const bool dostage = !last || has_next;
;       const u16* pa = last ? Abn : Ab + (t + 1) * BK;
;       const u16* pb = last ? Bbn : Bb + (t + 1) * BK;
;       bf16x8 Ar[3], Bq[2][4];
;       const unsigned la_u = lds0 + (unsigned)(cur * STAGE_B + aoff), lb_u = lds0 + (unsigned)(cur * STAGE_B + boff);
;     ...
;       DSR(Bq[0][0], lb_u, 0); DSR(Bq[0][1], lb_u, 2048); DSR(Bq[0][2], lb_u, 4096); DSR(Bq[0][3], lb_u, 6144);
;       DSR(Ar[0], la_u, 0); DSR(Ar[1], la_u, 2048);
;     ...
;       GSTEP(0, 2); GSTEP(1, 6); GSTEP(2, 6); GSTEP(3, 6); GSTEP(4, 2); GSTEP(5, 2); GSTEP(6, 2); GSTEP(7, 2);
;       GSTEP(8, 2); GSTEP(9, 2); GSTEP(10, 2); GSTEP(11, 2); GSTEP(12, 2); GSTEP(13, 2); GSTEP(14, 1); GSTEP(15, 0);
;       WAIT_V(0);
;       if (EPI != EPI_SS && t == 0 && tid < 256) rsl[tid] = rsq_(ssv * (1.f / DM) + EPS);
;       __syncthreads();
;     }
.Lss_sk3:
	ds_read_b128 v[160:163], v197 offset:10240
	s_waitcnt lgkmcnt(6)
	v_mfma_f32_16x16x32_bf16 v[76:79], v[164:167], v[212:215], v[76:79]
	v_mfma_f32_16x16x32_bf16 v[72:75], v[164:167], v[216:219], v[72:75]
	v_mfma_f32_16x16x32_bf16 v[68:71], v[164:167], v[220:223], v[68:71]
	v_mfma_f32_16x16x32_bf16 v[64:67], v[164:167], v[224:227], v[64:67]
	s_cbranch_vccz .Lss_sk4
	s_add_u32 m0, s29, 0xc000
	s_nop 0
	global_load_lds_dwordx4 v234, s[0:1]
	s_add_u32 m0, s29, 0xe000
	s_nop 0
	global_load_lds_dwordx4 v235, s[0:1]
.Lss_sk4:
	ds_read_b128 v[164:167], v197 offset:12288
	s_waitcnt lgkmcnt(2)
	v_mfma_f32_16x16x32_bf16 v[60:63], v[168:171], v[212:215], v[60:63]
	v_mfma_f32_16x16x32_bf16 v[56:59], v[168:171], v[216:219], v[56:59]
	v_mfma_f32_16x16x32_bf16 v[52:55], v[168:171], v[220:223], v[52:55]
	v_mfma_f32_16x16x32_bf16 v[48:51], v[168:171], v[224:227], v[48:51]
	ds_read_b128 v[168:171], v197 offset:14336
	s_waitcnt lgkmcnt(2)
	v_mfma_f32_16x16x32_bf16 v[44:47], v[160:163], v[212:215], v[44:47]
	v_mfma_f32_16x16x32_bf16 v[40:43], v[160:163], v[216:219], v[40:43]
	v_mfma_f32_16x16x32_bf16 v[36:39], v[160:163], v[220:223], v[36:39]
	v_mfma_f32_16x16x32_bf16 v[32:35], v[160:163], v[224:227], v[32:35]
	ds_read_b128 v[160:163], v197 offset:1024
	s_waitcnt lgkmcnt(2)
	v_mfma_f32_16x16x32_bf16 v[28:31], v[164:167], v[212:215], v[28:31]
	v_mfma_f32_16x16x32_bf16 v[24:27], v[164:167], v[216:219], v[24:27]
	v_mfma_f32_16x16x32_bf16 v[20:23], v[164:167], v[220:223], v[20:23]
	v_mfma_f32_16x16x32_bf16 v[16:19], v[164:167], v[224:227], v[16:19]
	ds_read_b128 v[164:167], v197 offset:3072
	s_waitcnt lgkmcnt(2)
	v_mfma_f32_16x16x32_bf16 v[12:15], v[168:171], v[212:215], v[12:15]
	v_mfma_f32_16x16x32_bf16 v[8:11], v[168:171], v[216:219], v[8:11]
	v_mfma_f32_16x16x32_bf16 v[4:7], v[168:171], v[220:223], v[4:7]
	v_mfma_f32_16x16x32_bf16 v[0:3], v[168:171], v[224:227], v[0:3]
	ds_read_b128 v[144:147], v197 offset:5120
	s_waitcnt lgkmcnt(2)
	v_mfma_f32_16x16x32_bf16 v[124:127], v[160:163], v[128:131], v[124:127]
	v_mfma_f32_16x16x32_bf16 v[120:123], v[160:163], v[132:135], v[120:123]
	v_mfma_f32_16x16x32_bf16 v[116:119], v[160:163], v[136:139], v[116:119]
	v_mfma_f32_16x16x32_bf16 v[112:115], v[160:163], v[140:143], v[112:115]
	ds_read_b128 v[148:151], v197 offset:7168
	s_waitcnt lgkmcnt(2)
	v_mfma_f32_16x16x32_bf16 v[108:111], v[164:167], v[128:131], v[108:111]
	v_mfma_f32_16x16x32_bf16 v[104:107], v[164:167], v[132:135], v[104:107]
	v_mfma_f32_16x16x32_bf16 v[100:103], v[164:167], v[136:139], v[100:103]
	v_mfma_f32_16x16x32_bf16 v[96:99], v[164:167], v[140:143], v[96:99]
	ds_read_b128 v[152:155], v197 offset:9216
	s_waitcnt lgkmcnt(2)
	v_mfma_f32_16x16x32_bf16 v[92:95], v[144:147], v[128:131], v[92:95]
	v_mfma_f32_16x16x32_bf16 v[88:91], v[144:147], v[132:135], v[88:91]
	v_mfma_f32_16x16x32_bf16 v[84:87], v[144:147], v[136:139], v[84:87]
	v_mfma_f32_16x16x32_bf16 v[80:83], v[144:147], v[140:143], v[80:83]
	ds_read_b128 v[144:147], v197 offset:11264
	s_waitcnt lgkmcnt(2)
	v_mfma_f32_16x16x32_bf16 v[76:79], v[148:151], v[128:131], v[76:79]
	v_mfma_f32_16x16x32_bf16 v[72:75], v[148:151], v[132:135], v[72:75]
	v_mfma_f32_16x16x32_bf16 v[68:71], v[148:151], v[136:139], v[68:71]
	v_mfma_f32_16x16x32_bf16 v[64:67], v[148:151], v[140:143], v[64:67]
	ds_read_b128 v[148:151], v197 offset:13312
	s_waitcnt lgkmcnt(2)
	v_mfma_f32_16x16x32_bf16 v[60:63], v[152:155], v[128:131], v[60:63]
	v_mfma_f32_16x16x32_bf16 v[56:59], v[152:155], v[132:135], v[56:59]
	v_mfma_f32_16x16x32_bf16 v[52:55], v[152:155], v[136:139], v[52:55]
	v_mfma_f32_16x16x32_bf16 v[48:51], v[152:155], v[140:143], v[48:51]
	ds_read_b128 v[152:155], v197 offset:15360
	s_waitcnt lgkmcnt(2)
	v_mfma_f32_16x16x32_bf16 v[44:47], v[144:147], v[128:131], v[44:47]
	v_mfma_f32_16x16x32_bf16 v[40:43], v[144:147], v[132:135], v[40:43]
	v_mfma_f32_16x16x32_bf16 v[36:39], v[144:147], v[136:139], v[36:39]
	v_mfma_f32_16x16x32_bf16 v[32:35], v[144:147], v[140:143], v[32:35]
	s_waitcnt vmcnt(0) lgkmcnt(0)
	s_barrier
	v_xor_b32_e32 v198, 0x10000, v198
	v_xor_b32_e32 v197, 0x10000, v197
	ds_read_b128 v[212:215], v198 offset:0
	ds_read_b128 v[216:219], v198 offset:2048
	ds_read_b128 v[220:223], v198 offset:4096
	ds_read_b128 v[224:227], v198 offset:6144
	ds_read_b128 v[228:231], v197 offset:0
	ds_read_b128 v[168:171], v197 offset:2048
	ds_read_b128 v[160:163], v197 offset:4096
	s_add_u32 s34, s34, 0x80
	s_addc_u32 s35, s35, 0
	s_add_u32 s0, s0, 0x80
	s_addc_u32 s1, s1, 0
	s_xor_b32 s29, s29, 0x10000
	s_add_i32 s30, s30, 1
	s_cmp_lg_u32 s30, -1
	s_cselect_b32 s34, s34, s10
	s_cselect_b32 s35, s35, s11
	s_cselect_b32 s0, s0, s6
	s_cselect_b32 s1, s1, s7
	s_cselect_b64 vcc, -1, s[12:13]
	s_cmp_eq_u32 s30, 0
	s_cselect_b64 vcc, 0, vcc
	v_mfma_f32_16x16x32_bf16 v[28:31], v[148:151], v[128:131], v[28:31]
	v_mfma_f32_16x16x32_bf16 v[24:27], v[148:151], v[132:135], v[24:27]
	v_mfma_f32_16x16x32_bf16 v[20:23], v[148:151], v[136:139], v[20:23]
	v_mfma_f32_16x16x32_bf16 v[16:19], v[148:151], v[140:143], v[16:19]
	v_mfma_f32_16x16x32_bf16 v[12:15], v[152:155], v[128:131], v[12:15]
	v_mfma_f32_16x16x32_bf16 v[8:11], v[152:155], v[132:135], v[8:11]
	v_mfma_f32_16x16x32_bf16 v[4:7], v[152:155], v[136:139], v[4:7]
	v_mfma_f32_16x16x32_bf16 v[0:3], v[152:155], v[140:143], v[0:3]
	s_cmp_lg_u32 s30, 0
	s_cbranch_scc1 .Lss_head
	s_waitcnt lgkmcnt(0)
	s_setprio 0
	v_mov_b32_e32 v128, v124
	v_mov_b32_e32 v129, v125
	v_mov_b32_e32 v130, v126
	v_mov_b32_e32 v131, v127
	v_mov_b32_e32 v132, v120
	v_mov_b32_e32 v133, v121
	v_mov_b32_e32 v134, v122
	v_mov_b32_e32 v135, v123
	v_mov_b32_e32 v136, v116
	v_mov_b32_e32 v137, v117
	v_mov_b32_e32 v138, v118
	v_mov_b32_e32 v139, v119
	v_mov_b32_e32 v140, v112
	v_mov_b32_e32 v141, v113
	v_mov_b32_e32 v142, v114
	v_mov_b32_e32 v143, v115
	v_mov_b32_e32 v148, v64
	v_mov_b32_e32 v149, v65
	v_mov_b32_e32 v150, v66
	v_mov_b32_e32 v151, v67
	s_branch .Lss_epi

; #define DSR(dst, addr, OFF) asm volatile("ds_read_b128 %0, %1 offset:%2" : "=&v"(dst) : "v"(addr), "i"(OFF) : "memory")
; template <int EPI>
; __device__ __forceinline__ void gemm_phase(const Params& p, const u16* __restrict__ A, const u16* __restrict__ Bt, int K, int nN,
;                            u16* __restrict__ Cout, int ldc) {
;     ...
;       bf16x8 Ar[3], Bq[2][4];
;       const unsigned la_u = lds0 + (unsigned)(cur * STAGE_B + aoff), lb_u = lds0 + (unsigned)(cur * STAGE_B + boff);
;     ...
;       DSR(Bq[0][0], lb_u, 0); DSR(Bq[0][1], lb_u, 2048); DSR(Bq[0][2], lb_u, 4096); DSR(Bq[0][3], lb_u, 6144);
;       DSR(Ar[0], la_u, 0); DSR(Ar[1], la_u, 2048);
;     ...
;       GSTEP(0, 2); GSTEP(1, 6); GSTEP(2, 6); GSTEP(3, 6); GSTEP(4, 2); GSTEP(5, 2); GSTEP(6, 2); GSTEP(7, 2);
;       GSTEP(8, 2); GSTEP(9, 2); GSTEP(10, 2); GSTEP(11, 2); GSTEP(12, 2); GSTEP(13, 2); GSTEP(14, 1); GSTEP(15, 0);
.LBB0_1131:
	ds_read_b128 v[0:3], v194 offset:0
	ds_read_b128 v[4:7], v194 offset:0x800
	ds_read_b128 v[8:11], v194 offset:0x1000
	ds_read_b128 v[12:15], v194 offset:0x1800
	ds_read_b128 v[16:19], v193 offset:0
	ds_read_b128 v[20:23], v193 offset:0x800
	ds_read_b128 v[24:27], v193 offset:0x1000
	s_waitcnt lgkmcnt(2)
	s_setprio 1
	v_mfma_f32_16x16x32_bf16 v[28:31], v[16:19], v[0:3], 0
	v_mfma_f32_16x16x32_bf16 v[32:35], v[16:19], v[4:7], 0
	v_mfma_f32_16x16x32_bf16 v[36:39], v[16:19], v[8:11], 0
	v_mfma_f32_16x16x32_bf16 v[16:19], v[16:19], v[12:15], 0
	s_setprio 0
	v_mov_b32_e32 v40, v176
	v_mov_b32_e32 v41, v172
	v_lshl_add_u64 v[40:41], v[40:41], 1, s[24:25]
	v_readfirstlane_b32 s13, v198
	v_lshl_add_u64 v[40:41], v[40:41], 0, s[62:63]
	s_mov_b32 m0, s13
	s_nop 0
	global_load_lds_dwordx4 v[40:41], off
	ds_read_b128 v[40:43], v193 offset:0x1800
	ds_read_b128 v[130:133], v194 offset:0x400
	ds_read_b128 v[134:137], v194 offset:0xc00
	ds_read_b128 v[138:141], v194 offset:0x1400
	ds_read_b128 v[142:145], v194 offset:0x1c00
	s_waitcnt lgkmcnt(6)
	s_setprio 1
	v_mfma_f32_16x16x32_bf16 v[44:47], v[20:23], v[0:3], 0
	v_mfma_f32_16x16x32_bf16 v[48:51], v[20:23], v[4:7], 0
	v_mfma_f32_16x16x32_bf16 v[52:55], v[20:23], v[8:11], 0
	v_mfma_f32_16x16x32_bf16 v[20:23], v[20:23], v[12:15], 0
	s_setprio 0
	v_mov_b32_e32 v56, v178
	v_mov_b32_e32 v57, v172
	v_lshl_add_u64 v[56:57], v[56:57], 1, s[24:25]
	v_readfirstlane_b32 s13, v199
	v_lshl_add_u64 v[56:57], v[56:57], 0, s[62:63]
	s_mov_b32 m0, s13
	s_nop 0
	global_load_lds_dwordx4 v[56:57], off
	ds_read_b128 v[56:59], v193 offset:0x2000
	s_waitcnt lgkmcnt(6)
	s_setprio 1
	v_mfma_f32_16x16x32_bf16 v[60:63], v[24:27], v[0:3], 0
	v_mfma_f32_16x16x32_bf16 v[64:67], v[24:27], v[4:7], 0
	v_mfma_f32_16x16x32_bf16 v[68:71], v[24:27], v[8:11], 0
	v_mfma_f32_16x16x32_bf16 v[24:27], v[24:27], v[12:15], 0
	s_setprio 0
	v_mov_b32_e32 v72, v180
	v_mov_b32_e32 v73, v172
	v_lshl_add_u64 v[72:73], v[72:73], 1, s[24:25]
	v_readfirstlane_b32 s13, v200
	v_lshl_add_u64 v[72:73], v[72:73], 0, s[62:63]
	s_mov_b32 m0, s13
	s_nop 0
	global_load_lds_dwordx4 v[72:73], off
	ds_read_b128 v[72:75], v193 offset:0x2800
	s_waitcnt lgkmcnt(6)
	s_setprio 1
	v_mfma_f32_16x16x32_bf16 v[76:79], v[40:43], v[0:3], 0
	v_mfma_f32_16x16x32_bf16 v[146:149], v[40:43], v[4:7], 0
	v_mfma_f32_16x16x32_bf16 v[150:153], v[40:43], v[8:11], 0
	v_mfma_f32_16x16x32_bf16 v[40:43], v[40:43], v[12:15], 0
	s_setprio 0
	v_mov_b32_e32 v80, v191
	v_mov_b32_e32 v81, v172
	v_lshl_add_u64 v[80:81], v[80:81], 1, s[24:25]
	v_readfirstlane_b32 s13, v201
	v_lshl_add_u64 v[80:81], v[80:81], 0, s[62:63]
	s_mov_b32 m0, s13
	s_nop 0
	global_load_lds_dwordx4 v[80:81], off
	ds_read_b128 v[80:83], v193 offset:0x3000
	s_waitcnt lgkmcnt(2)
	s_setprio 1
	v_mfma_f32_16x16x32_bf16 v[154:157], v[56:59], v[0:3], 0
	v_mfma_f32_16x16x32_bf16 v[158:161], v[56:59], v[4:7], 0
	v_mfma_f32_16x16x32_bf16 v[162:165], v[56:59], v[8:11], 0
	v_mfma_f32_16x16x32_bf16 v[166:169], v[56:59], v[12:15], 0
	s_setprio 0
	v_mov_b32_e32 v56, v176
	v_mov_b32_e32 v57, v172
	v_lshl_add_u64 v[56:57], v[56:57], 1, s[22:23]
	v_readfirstlane_b32 s13, v205
	v_lshl_add_u64 v[56:57], v[56:57], 0, s[62:63]
	s_mov_b32 m0, s13
	s_nop 0
	global_load_lds_dwordx4 v[56:57], off
	ds_read_b128 v[56:59], v193 offset:0x3800
	s_waitcnt lgkmcnt(2)
	s_setprio 1
	v_mfma_f32_16x16x32_bf16 v[206:209], v[72:75], v[0:3], 0
	v_mfma_f32_16x16x32_bf16 v[210:213], v[72:75], v[4:7], 0
	v_mfma_f32_16x16x32_bf16 v[214:217], v[72:75], v[8:11], 0
	v_mfma_f32_16x16x32_bf16 v[218:221], v[72:75], v[12:15], 0
	s_setprio 0
	v_mov_b32_e32 v72, v178
	v_mov_b32_e32 v73, v172
	v_lshl_add_u64 v[72:73], v[72:73], 1, s[22:23]
	v_readfirstlane_b32 s13, v202
	v_lshl_add_u64 v[72:73], v[72:73], 0, s[62:63]
	s_mov_b32 m0, s13
	s_nop 0
	global_load_lds_dwordx4 v[72:73], off
	ds_read_b128 v[72:75], v193 offset:0x400
	s_waitcnt lgkmcnt(2)
	s_setprio 1
	v_mfma_f32_16x16x32_bf16 v[222:225], v[80:83], v[0:3], 0
	v_mfma_f32_16x16x32_bf16 v[226:229], v[80:83], v[4:7], 0
	v_mfma_f32_16x16x32_bf16 v[230:233], v[80:83], v[8:11], 0
	v_mfma_f32_16x16x32_bf16 v[234:237], v[80:83], v[12:15], 0
	s_setprio 0
	v_mov_b32_e32 v80, v180
	v_mov_b32_e32 v81, v172
	v_lshl_add_u64 v[80:81], v[80:81], 1, s[22:23]
	v_readfirstlane_b32 s13, v203
	v_lshl_add_u64 v[80:81], v[80:81], 0, s[62:63]
	s_mov_b32 m0, s13
	s_nop 0
	global_load_lds_dwordx4 v[80:81], off
	ds_read_b128 v[80:83], v193 offset:0xc00
	s_waitcnt lgkmcnt(2)
	s_setprio 1
	v_mfma_f32_16x16x32_bf16 v[0:3], v[56:59], v[0:3], 0
	v_mfma_f32_16x16x32_bf16 v[4:7], v[56:59], v[4:7], 0
	v_mfma_f32_16x16x32_bf16 v[238:241], v[56:59], v[8:11], 0
	v_mfma_f32_16x16x32_bf16 v[242:245], v[56:59], v[12:15], 0
	s_setprio 0
	v_mov_b32_e32 v8, v191
	v_mov_b32_e32 v9, v172
	v_lshl_add_u64 v[8:9], v[8:9], 1, s[22:23]
	v_readfirstlane_b32 s13, v204
	v_lshl_add_u64 v[8:9], v[8:9], 0, s[62:63]
	s_mov_b32 m0, s13
	s_nop 0
	global_load_lds_dwordx4 v[8:9], off
	ds_read_b128 v[8:11], v193 offset:0x1400
	s_waitcnt lgkmcnt(2)
	s_setprio 1
	v_mfma_f32_16x16x32_bf16 v[124:127], v[72:75], v[130:133], v[28:31]
	v_mfma_f32_16x16x32_bf16 v[120:123], v[72:75], v[134:137], v[32:35]
	v_mfma_f32_16x16x32_bf16 v[116:119], v[72:75], v[138:141], v[36:39]
	v_mfma_f32_16x16x32_bf16 v[112:115], v[72:75], v[142:145], v[16:19]
	s_setprio 0
	ds_read_b128 v[12:15], v193 offset:0x1c00
	s_waitcnt lgkmcnt(2)
	s_setprio 1
	v_mfma_f32_16x16x32_bf16 v[108:111], v[80:83], v[130:133], v[44:47]
	v_mfma_f32_16x16x32_bf16 v[104:107], v[80:83], v[134:137], v[48:51]
	v_mfma_f32_16x16x32_bf16 v[100:103], v[80:83], v[138:141], v[52:55]
	v_mfma_f32_16x16x32_bf16 v[96:99], v[80:83], v[142:145], v[20:23]
	s_setprio 0
	ds_read_b128 v[16:19], v193 offset:0x2400
	s_waitcnt lgkmcnt(2)
; __device__ __forceinline__ float rsq_(float x) { return __builtin_amdgcn_rsqf(x); }
; #define WAIT_V(n) asm volatile("s_waitcnt vmcnt(%0)" ::"n"(n) : "memory")
; #define DSR(dst, addr, OFF) asm volatile("ds_read_b128 %0, %1 offset:%2" : "=&v"(dst) : "v"(addr), "i"(OFF) : "memory")
; template <int EPI>
; __device__ __forceinline__ void gemm_phase(const Params& p, const u16* __restrict__ A, const u16* __restrict__ Bt, int K, int nN,
;                            u16* __restrict__ Cout, int ldc) {
;     ...
;     for (int t = 0; t < nt; ++t) {
;       const int cur = t & 1, nb = cur ^ 1;
;       const bool last = (t + 1 == nt);
;       const bool dostage = !last || has_next;
;       const u16* pa = last ? Abn : Ab + (t + 1) * BK;
;       const u16* pb = last ? Bbn : Bb + (t + 1) * BK;
;       bf16x8 Ar[3], Bq[2][4];
;       const unsigned la_u = lds0 + (unsigned)(cur * STAGE_B + aoff), lb_u = lds0 + (unsigned)(cur * STAGE_B + boff);
;     ...
;       DSR(Bq[0][0], lb_u, 0); DSR(Bq[0][1], lb_u, 2048); DSR(Bq[0][2], lb_u, 4096); DSR(Bq[0][3], lb_u, 6144);
;       DSR(Ar[0], la_u, 0); DSR(Ar[1], la_u, 2048);
;     ...
;       GSTEP(0, 2); GSTEP(1, 6); GSTEP(2, 6); GSTEP(3, 6); GSTEP(4, 2); GSTEP(5, 2); GSTEP(6, 2); GSTEP(7, 2);
;       GSTEP(8, 2); GSTEP(9, 2); GSTEP(10, 2); GSTEP(11, 2); GSTEP(12, 2); GSTEP(13, 2); GSTEP(14, 1); GSTEP(15, 0);
;       WAIT_V(0);
;       if (EPI != EPI_SS && t == 0 && tid < 256) rsl[tid] = rsq_(ssv * (1.f / DM) + EPS);
;       __syncthreads();
	s_setprio 1
	v_mfma_f32_16x16x32_bf16 v[92:95], v[8:11], v[130:133], v[60:63]
	v_mfma_f32_16x16x32_bf16 v[88:91], v[8:11], v[134:137], v[64:67]
	v_mfma_f32_16x16x32_bf16 v[84:87], v[8:11], v[138:141], v[68:71]
	v_mfma_f32_16x16x32_bf16 v[80:83], v[8:11], v[142:145], v[24:27]
	s_setprio 0
	ds_read_b128 v[8:11], v193 offset:0x2c00
	s_waitcnt lgkmcnt(2)
	s_setprio 1
	v_mfma_f32_16x16x32_bf16 v[76:79], v[12:15], v[130:133], v[76:79]
	v_mfma_f32_16x16x32_bf16 v[72:75], v[12:15], v[134:137], v[146:149]
	v_mfma_f32_16x16x32_bf16 v[68:71], v[12:15], v[138:141], v[150:153]
	v_mfma_f32_16x16x32_bf16 v[64:67], v[12:15], v[142:145], v[40:43]
	s_setprio 0
	ds_read_b128 v[12:15], v193 offset:0x3400
	s_waitcnt lgkmcnt(2)
	s_setprio 1
	v_mfma_f32_16x16x32_bf16 v[60:63], v[16:19], v[130:133], v[154:157]
	v_mfma_f32_16x16x32_bf16 v[56:59], v[16:19], v[134:137], v[158:161]
	v_mfma_f32_16x16x32_bf16 v[52:55], v[16:19], v[138:141], v[162:165]
	v_mfma_f32_16x16x32_bf16 v[48:51], v[16:19], v[142:145], v[166:169]
	s_setprio 0
	ds_read_b128 v[146:149], v193 offset:0x3c00
	s_waitcnt lgkmcnt(2)
	s_setprio 1
	v_mfma_f32_16x16x32_bf16 v[44:47], v[8:11], v[130:133], v[206:209]
	v_mfma_f32_16x16x32_bf16 v[40:43], v[8:11], v[134:137], v[210:213]
	v_mfma_f32_16x16x32_bf16 v[36:39], v[8:11], v[138:141], v[214:217]
	v_mfma_f32_16x16x32_bf16 v[32:35], v[8:11], v[142:145], v[218:221]
	s_setprio 0
	s_waitcnt lgkmcnt(1)
	s_setprio 1
	v_mfma_f32_16x16x32_bf16 v[28:31], v[12:15], v[130:133], v[222:225]
	v_mfma_f32_16x16x32_bf16 v[24:27], v[12:15], v[134:137], v[226:229]
	v_mfma_f32_16x16x32_bf16 v[20:23], v[12:15], v[138:141], v[230:233]
	v_mfma_f32_16x16x32_bf16 v[16:19], v[12:15], v[142:145], v[234:237]
	s_setprio 0
	s_waitcnt lgkmcnt(0)
	s_setprio 1
	v_mfma_f32_16x16x32_bf16 v[12:15], v[146:149], v[130:133], v[0:3]
	v_mfma_f32_16x16x32_bf16 v[8:11], v[146:149], v[134:137], v[4:7]
	v_mfma_f32_16x16x32_bf16 v[4:7], v[146:149], v[138:141], v[238:241]
	v_mfma_f32_16x16x32_bf16 v[0:3], v[146:149], v[142:145], v[242:245]
	s_setprio 0
	s_waitcnt vmcnt(0)
	s_and_saveexec_b64 s[22:23], s[0:1]
	v_fmamk_f32 v128, v128, 0x3a800000, v183
	s_nop 0
	v_rsq_f32_e32 v128, v128
	s_nop 0
	ds_write_b32 v195, v128
	s_or_b64 exec, exec, s[22:23]
	s_add_u32 s13, s35, s20
	s_addc_u32 s24, s36, s21
	s_add_u32 s25, s37, s2
	s_addc_u32 s26, s38, s3
	s_mov_b32 s27, -15
	s_waitcnt vmcnt(0) lgkmcnt(0)
	s_barrier
	v_readfirstlane_b32 s28, v175
	s_nop 3
	s_lshr_b32 s28, s28, 12
	s_cmp_eq_u32 s28, 1
	s_cbranch_scc0 .Lgu_prio
	s_setprio 1
.Lgu_prio:
	v_or_b32_e32 v208, 0x10000, v194
	v_add_u32_e32 v206, 0x10000, v193
	ds_read_b128 v[212:215], v208 offset:0
	ds_read_b128 v[216:219], v208 offset:2048
	ds_read_b128 v[220:223], v208 offset:4096
	ds_read_b128 v[224:227], v208 offset:6144
	ds_read_b128 v[228:231], v206 offset:0
	ds_read_b128 v[168:171], v206 offset:2048
	ds_read_b128 v[160:163], v206 offset:4096
	v_readfirstlane_b32 s40, v175
	v_lshlrev_b32_e32 v232, 1, v176
	v_lshlrev_b32_e32 v233, 1, v178
	v_lshlrev_b32_e32 v234, 1, v180
	v_lshlrev_b32_e32 v235, 1, v191
	s_cmp_lg_u32 s27, -1
	s_cselect_b32 s22, s25, s16
	s_cselect_b32 s23, s26, s17
	s_cselect_b32 s20, s13, s18
	s_cselect_b32 s21, s24, s19
	s_cselect_b64 vcc, -1, s[10:11]
.Lgu_head:
	s_waitcnt lgkmcnt(2)
	v_mfma_f32_16x16x32_bf16 v[124:127], v[228:231], v[212:215], v[124:127]
	v_mfma_f32_16x16x32_bf16 v[120:123], v[228:231], v[216:219], v[120:123]
	v_mfma_f32_16x16x32_bf16 v[116:119], v[228:231], v[220:223], v[116:119]
	v_mfma_f32_16x16x32_bf16 v[112:115], v[228:231], v[224:227], v[112:115]
	s_cbranch_vccz .Lgu_sk5
	s_mov_b32 m0, s40
	s_nop 0
	global_load_lds_dwordx4 v232, s[22:23]
	s_add_u32 m0, s40, 0x2000
	s_nop 0
	global_load_lds_dwordx4 v233, s[22:23]
.Lgu_sk5:
	ds_read_b128 v[164:167], v206 offset:6144
	ds_read_b128 v[128:131], v208 offset:1024
	ds_read_b128 v[132:135], v208 offset:3072
	ds_read_b128 v[136:139], v208 offset:5120
	ds_read_b128 v[140:143], v208 offset:7168
	s_waitcnt lgkmcnt(6)
	v_mfma_f32_16x16x32_bf16 v[108:111], v[168:171], v[212:215], v[108:111]
	v_mfma_f32_16x16x32_bf16 v[104:107], v[168:171], v[216:219], v[104:107]
	v_mfma_f32_16x16x32_bf16 v[100:103], v[168:171], v[220:223], v[100:103]
	v_mfma_f32_16x16x32_bf16 v[96:99], v[168:171], v[224:227], v[96:99]
	s_cbranch_vccz .Lgu_sk6
	s_add_u32 m0, s40, 0x4000
	s_nop 0
	global_load_lds_dwordx4 v234, s[22:23]
	s_add_u32 m0, s40, 0x6000
	s_nop 0
	global_load_lds_dwordx4 v235, s[22:23]
.Lgu_sk6:
	ds_read_b128 v[168:171], v206 offset:8192
	s_waitcnt lgkmcnt(6)
	v_mfma_f32_16x16x32_bf16 v[92:95], v[160:163], v[212:215], v[92:95]
	v_mfma_f32_16x16x32_bf16 v[88:91], v[160:163], v[216:219], v[88:91]
	v_mfma_f32_16x16x32_bf16 v[84:87], v[160:163], v[220:223], v[84:87]
	v_mfma_f32_16x16x32_bf16 v[80:83], v[160:163], v[224:227], v[80:83]
	s_cbranch_vccz .Lgu_sk7
	s_add_u32 m0, s40, 0x8000
	s_nop 0
	global_load_lds_dwordx4 v232, s[20:21]
	s_add_u32 m0, s40, 0xa000
	s_nop 0
	global_load_lds_dwordx4 v233, s[20:21]
; __device__ __forceinline__ float rsq_(float x) { return __builtin_amdgcn_rsqf(x); }
; #define WAIT_V(n) asm volatile("s_waitcnt vmcnt(%0)" ::"n"(n) : "memory")
; #define DSR(dst, addr, OFF) asm volatile("ds_read_b128 %0, %1 offset:%2" : "=&v"(dst) : "v"(addr), "i"(OFF) : "memory")
; template <int EPI>
; __device__ __forceinline__ void gemm_phase(const Params& p, const u16* __restrict__ A, const u16* __restrict__ Bt, int K, int nN,
;                            u16* __restrict__ Cout, int ldc) {
;     ...
;     for (int t = 0; t < nt; ++t) {
;       const int cur = t & 1, nb = cur ^ 1;
;       const bool last = (t + 1 == nt);
;       const bool dostage = !last || has_next;
;       const u16* pa = last ? Abn : Ab + (t + 1) * BK;
;       const u16* pb = last ? Bbn : Bb + (t + 1) * BK;
;       bf16x8 Ar[3], Bq[2][4];
;       const unsigned la_u = lds0 + (unsigned)(cur * STAGE_B + aoff), lb_u = lds0 + (unsigned)(cur * STAGE_B + boff);
;     ...
;       DSR(Bq[0][0], lb_u, 0); DSR(Bq[0][1], lb_u, 2048); DSR(Bq[0][2], lb_u, 4096); DSR(Bq[0][3], lb_u, 6144);
;       DSR(Ar[0], la_u, 0); DSR(Ar[1], la_u, 2048);
;     ...
;       GSTEP(0, 2); GSTEP(1, 6); GSTEP(2, 6); GSTEP(3, 6); GSTEP(4, 2); GSTEP(5, 2); GSTEP(6, 2); GSTEP(7, 2);
;       GSTEP(8, 2); GSTEP(9, 2); GSTEP(10, 2); GSTEP(11, 2); GSTEP(12, 2); GSTEP(13, 2); GSTEP(14, 1); GSTEP(15, 0);
;       WAIT_V(0);
;       if (EPI != EPI_SS && t == 0 && tid < 256) rsl[tid] = rsq_(ssv * (1.f / DM) + EPS);
;       __syncthreads();
.Lgu_sk7:
	ds_read_b128 v[160:163], v206 offset:10240
	s_waitcnt lgkmcnt(6)
	v_mfma_f32_16x16x32_bf16 v[76:79], v[164:167], v[212:215], v[76:79]
	v_mfma_f32_16x16x32_bf16 v[72:75], v[164:167], v[216:219], v[72:75]
	v_mfma_f32_16x16x32_bf16 v[68:71], v[164:167], v[220:223], v[68:71]
	v_mfma_f32_16x16x32_bf16 v[64:67], v[164:167], v[224:227], v[64:67]
	s_cbranch_vccz .Lgu_sk8
	s_add_u32 m0, s40, 0xc000
	s_nop 0
	global_load_lds_dwordx4 v234, s[20:21]
	s_add_u32 m0, s40, 0xe000
	s_nop 0
	global_load_lds_dwordx4 v235, s[20:21]
.Lgu_sk8:
	ds_read_b128 v[164:167], v206 offset:12288
	s_waitcnt lgkmcnt(2)
	v_mfma_f32_16x16x32_bf16 v[60:63], v[168:171], v[212:215], v[60:63]
	v_mfma_f32_16x16x32_bf16 v[56:59], v[168:171], v[216:219], v[56:59]
	v_mfma_f32_16x16x32_bf16 v[52:55], v[168:171], v[220:223], v[52:55]
	v_mfma_f32_16x16x32_bf16 v[48:51], v[168:171], v[224:227], v[48:51]
	ds_read_b128 v[168:171], v206 offset:14336
	s_waitcnt lgkmcnt(2)
	v_mfma_f32_16x16x32_bf16 v[44:47], v[160:163], v[212:215], v[44:47]
	v_mfma_f32_16x16x32_bf16 v[40:43], v[160:163], v[216:219], v[40:43]
	v_mfma_f32_16x16x32_bf16 v[36:39], v[160:163], v[220:223], v[36:39]
	v_mfma_f32_16x16x32_bf16 v[32:35], v[160:163], v[224:227], v[32:35]
	ds_read_b128 v[160:163], v206 offset:1024
	s_waitcnt lgkmcnt(2)
	v_mfma_f32_16x16x32_bf16 v[28:31], v[164:167], v[212:215], v[28:31]
	v_mfma_f32_16x16x32_bf16 v[24:27], v[164:167], v[216:219], v[24:27]
	v_mfma_f32_16x16x32_bf16 v[20:23], v[164:167], v[220:223], v[20:23]
	v_mfma_f32_16x16x32_bf16 v[16:19], v[164:167], v[224:227], v[16:19]
	ds_read_b128 v[164:167], v206 offset:3072
	s_waitcnt lgkmcnt(2)
	v_mfma_f32_16x16x32_bf16 v[12:15], v[168:171], v[212:215], v[12:15]
	v_mfma_f32_16x16x32_bf16 v[8:11], v[168:171], v[216:219], v[8:11]
	v_mfma_f32_16x16x32_bf16 v[4:7], v[168:171], v[220:223], v[4:7]
	v_mfma_f32_16x16x32_bf16 v[0:3], v[168:171], v[224:227], v[0:3]
	ds_read_b128 v[144:147], v206 offset:5120
	s_waitcnt lgkmcnt(2)
	v_mfma_f32_16x16x32_bf16 v[124:127], v[160:163], v[128:131], v[124:127]
	v_mfma_f32_16x16x32_bf16 v[120:123], v[160:163], v[132:135], v[120:123]
	v_mfma_f32_16x16x32_bf16 v[116:119], v[160:163], v[136:139], v[116:119]
	v_mfma_f32_16x16x32_bf16 v[112:115], v[160:163], v[140:143], v[112:115]
	ds_read_b128 v[148:151], v206 offset:7168
	s_waitcnt lgkmcnt(2)
	v_mfma_f32_16x16x32_bf16 v[108:111], v[164:167], v[128:131], v[108:111]
	v_mfma_f32_16x16x32_bf16 v[104:107], v[164:167], v[132:135], v[104:107]
	v_mfma_f32_16x16x32_bf16 v[100:103], v[164:167], v[136:139], v[100:103]
	v_mfma_f32_16x16x32_bf16 v[96:99], v[164:167], v[140:143], v[96:99]
	ds_read_b128 v[152:155], v206 offset:9216
	s_waitcnt lgkmcnt(2)
	v_mfma_f32_16x16x32_bf16 v[92:95], v[144:147], v[128:131], v[92:95]
	v_mfma_f32_16x16x32_bf16 v[88:91], v[144:147], v[132:135], v[88:91]
	v_mfma_f32_16x16x32_bf16 v[84:87], v[144:147], v[136:139], v[84:87]
	v_mfma_f32_16x16x32_bf16 v[80:83], v[144:147], v[140:143], v[80:83]
	ds_read_b128 v[144:147], v206 offset:11264
	s_waitcnt lgkmcnt(2)
	v_mfma_f32_16x16x32_bf16 v[76:79], v[148:151], v[128:131], v[76:79]
	v_mfma_f32_16x16x32_bf16 v[72:75], v[148:151], v[132:135], v[72:75]
	v_mfma_f32_16x16x32_bf16 v[68:71], v[148:151], v[136:139], v[68:71]
	v_mfma_f32_16x16x32_bf16 v[64:67], v[148:151], v[140:143], v[64:67]
	ds_read_b128 v[148:151], v206 offset:13312
	s_waitcnt lgkmcnt(2)
	v_mfma_f32_16x16x32_bf16 v[60:63], v[152:155], v[128:131], v[60:63]
	v_mfma_f32_16x16x32_bf16 v[56:59], v[152:155], v[132:135], v[56:59]
	v_mfma_f32_16x16x32_bf16 v[52:55], v[152:155], v[136:139], v[52:55]
	v_mfma_f32_16x16x32_bf16 v[48:51], v[152:155], v[140:143], v[48:51]
	ds_read_b128 v[152:155], v206 offset:15360
	s_waitcnt lgkmcnt(2)
	v_mfma_f32_16x16x32_bf16 v[44:47], v[144:147], v[128:131], v[44:47]
	v_mfma_f32_16x16x32_bf16 v[40:43], v[144:147], v[132:135], v[40:43]
	v_mfma_f32_16x16x32_bf16 v[36:39], v[144:147], v[136:139], v[36:39]
	v_mfma_f32_16x16x32_bf16 v[32:35], v[144:147], v[140:143], v[32:35]
	s_waitcnt vmcnt(0) lgkmcnt(0)
	s_barrier
	v_xor_b32_e32 v208, 0x10000, v208
	v_xor_b32_e32 v206, 0x10000, v206
	ds_read_b128 v[212:215], v208 offset:0
	ds_read_b128 v[216:219], v208 offset:2048
	ds_read_b128 v[220:223], v208 offset:4096
	ds_read_b128 v[224:227], v208 offset:6144
	ds_read_b128 v[228:231], v206 offset:0
	ds_read_b128 v[168:171], v206 offset:2048
	ds_read_b128 v[160:163], v206 offset:4096
	s_add_u32 s25, s25, 0x80
	s_addc_u32 s26, s26, 0
	s_add_u32 s13, s13, 0x80
	s_addc_u32 s24, s24, 0
	s_xor_b32 s40, s40, 0x10000
	s_add_i32 s27, s27, 1
	s_cmp_lg_u32 s27, -1
	s_cselect_b32 s22, s25, s16
	s_cselect_b32 s23, s26, s17
	s_cselect_b32 s20, s13, s18
	s_cselect_b32 s21, s24, s19
	s_cselect_b64 vcc, -1, s[10:11]
	s_cmp_eq_u32 s27, 0
	s_cselect_b64 vcc, 0, vcc
	v_mfma_f32_16x16x32_bf16 v[28:31], v[148:151], v[128:131], v[28:31]
	v_mfma_f32_16x16x32_bf16 v[24:27], v[148:151], v[132:135], v[24:27]
	v_mfma_f32_16x16x32_bf16 v[20:23], v[148:151], v[136:139], v[20:23]
	v_mfma_f32_16x16x32_bf16 v[16:19], v[148:151], v[140:143], v[16:19]
	v_mfma_f32_16x16x32_bf16 v[12:15], v[152:155], v[128:131], v[12:15]
	v_mfma_f32_16x16x32_bf16 v[8:11], v[152:155], v[132:135], v[8:11]
	v_mfma_f32_16x16x32_bf16 v[4:7], v[152:155], v[136:139], v[4:7]
	v_mfma_f32_16x16x32_bf16 v[0:3], v[152:155], v[140:143], v[0:3]
	s_cmp_lg_u32 s27, 0
	s_cbranch_scc1 .Lgu_head
	s_waitcnt lgkmcnt(0)
	s_setprio 0
	s_branch .LBB0_1126
